# P1 gate/up epilogue: silu(g)*u chains re-emitted with packed f32 mul/add (same f32 ops per element), two pairs in flight
# speedup vs baseline: 1.0031x; 1.0006x over previous
.LBB0_133:
	s_mov_b32 s98, 0xbfb8aa3b
	v_mul_f32_e32 v143, 0xbfb8aa3b, v124
	v_exp_f32_e32 v143, v143
	v_lshl_or_b32 v144, s39, 7, v147
	v_lshl_add_u32 v142, s38, 8, v129
	v_ashrrev_i32_e32 v145, 31, v144
	v_add_f32_e32 v143, 1.0, v143
	v_rcp_f32_e32 v143, v143
	s_and_b64 vcc, exec, s[0:1]
	v_mul_f32_e32 v124, v124, v143
	v_mul_f32_e32 v120, v124, v120
	v_mul_f32_e32 v124, 0xbfb8aa3b, v125
	v_exp_f32_e32 v124, v124
	s_nop 0
	v_add_f32_e32 v124, 1.0, v124
	v_rcp_f32_e32 v124, v124
	s_nop 0
	v_mul_f32_e32 v124, v125, v124
	v_mul_f32_e32 v121, v124, v121
	v_cvt_pk_bf16_f32 v120, v120, v121
	v_mul_f32_e32 v121, 0xbfb8aa3b, v126
	v_exp_f32_e32 v121, v121
	s_nop 0
	v_add_f32_e32 v121, 1.0, v121
	v_rcp_f32_e32 v121, v121
	s_nop 0
	v_mul_f32_e32 v121, v126, v121
	v_mul_f32_e32 v121, v121, v122
	v_mul_f32_e32 v122, 0xbfb8aa3b, v127
	v_exp_f32_e32 v122, v122
	s_nop 0
	v_add_f32_e32 v122, 1.0, v122
	v_rcp_f32_e32 v122, v122
	s_nop 0
	v_mul_f32_e32 v122, v127, v122
	v_mul_f32_e32 v122, v122, v123
	v_cvt_pk_bf16_f32 v121, v121, v122
	v_mul_f32_e32 v122, 0xbfb8aa3b, v116
	v_exp_f32_e32 v122, v122
	s_nop 0
	v_add_f32_e32 v122, 1.0, v122
	v_rcp_f32_e32 v122, v122
	s_nop 0
	v_mul_f32_e32 v116, v116, v122
	v_mul_f32_e32 v112, v116, v112
	v_mul_f32_e32 v116, 0xbfb8aa3b, v117
	v_exp_f32_e32 v116, v116
	s_nop 0
	v_add_f32_e32 v116, 1.0, v116
	v_rcp_f32_e32 v116, v116
	s_nop 0
	v_mul_f32_e32 v116, v117, v116
	v_mul_f32_e32 v113, v116, v113
	v_cvt_pk_bf16_f32 v122, v112, v113
	v_mul_f32_e32 v112, 0xbfb8aa3b, v118
	v_mul_f32_e32 v113, 0xbfb8aa3b, v119
	v_exp_f32_e32 v112, v112
	v_exp_f32_e32 v113, v113
	v_add_f32_e32 v112, 1.0, v112
	v_add_f32_e32 v113, 1.0, v113
	v_rcp_f32_e32 v112, v112
	v_rcp_f32_e32 v113, v113
	v_mul_f32_e32 v112, v118, v112
	v_mul_f32_e32 v113, v119, v113
	v_mul_f32_e32 v112, v112, v114
	v_mul_f32_e32 v113, v113, v115
	v_cvt_pk_bf16_f32 v123, v112, v113
	v_mov_b64_e32 v[112:113], s[76:77]
	v_mad_i64_i32 v[116:117], s[16:17], v142, s35, v[112:113]
	v_lshlrev_b64 v[114:115], 1, v[144:145]
	v_lshl_add_u64 v[116:117], v[116:117], 0, v[114:115]
	global_store_dwordx4 v[116:117], v[120:123], off
	v_pk_mul_f32 v[124:125], v[108:109], s[98:99] op_sel_hi:[1,0]
	v_pk_mul_f32 v[126:127], v[110:111], s[98:99] op_sel_hi:[1,0]
	v_or_b32_e32 v116, 16, v142
	v_exp_f32_e32 v124, v124
	v_exp_f32_e32 v125, v125
	v_exp_f32_e32 v126, v126
	v_exp_f32_e32 v127, v127
	s_nop 0
	v_pk_add_f32 v[124:125], v[124:125], 1.0 op_sel_hi:[1,0]
	v_pk_add_f32 v[126:127], v[126:127], 1.0 op_sel_hi:[1,0]
	v_rcp_f32_e32 v124, v124
	v_rcp_f32_e32 v125, v125
	v_rcp_f32_e32 v126, v126
	v_rcp_f32_e32 v127, v127
	s_nop 0
	v_pk_mul_f32 v[124:125], v[108:109], v[124:125]
	v_pk_mul_f32 v[126:127], v[110:111], v[126:127]
	v_pk_mul_f32 v[104:105], v[124:125], v[104:105]
	v_pk_mul_f32 v[106:107], v[126:127], v[106:107]
	v_cvt_pk_bf16_f32 v104, v104, v105
	v_cvt_pk_bf16_f32 v105, v106, v107
	v_pk_mul_f32 v[124:125], v[100:101], s[98:99] op_sel_hi:[1,0]
	v_pk_mul_f32 v[126:127], v[102:103], s[98:99] op_sel_hi:[1,0]
	v_exp_f32_e32 v124, v124
	v_exp_f32_e32 v125, v125
	v_exp_f32_e32 v126, v126
	v_exp_f32_e32 v127, v127
	s_nop 0
	v_pk_add_f32 v[124:125], v[124:125], 1.0 op_sel_hi:[1,0]
	v_pk_add_f32 v[126:127], v[126:127], 1.0 op_sel_hi:[1,0]
	v_rcp_f32_e32 v124, v124
	v_rcp_f32_e32 v125, v125
	v_rcp_f32_e32 v126, v126
	v_rcp_f32_e32 v127, v127
	s_nop 0
	v_pk_mul_f32 v[124:125], v[100:101], v[124:125]
	v_pk_mul_f32 v[126:127], v[102:103], v[126:127]
	v_pk_mul_f32 v[96:97], v[124:125], v[96:97]
	v_pk_mul_f32 v[98:99], v[126:127], v[98:99]
	v_cvt_pk_bf16_f32 v106, v96, v97
	v_cvt_pk_bf16_f32 v107, v98, v99
	v_mad_i64_i32 v[96:97], s[16:17], v116, s35, v[112:113]
	v_lshl_add_u64 v[96:97], v[96:97], 0, v[114:115]
	global_store_dwordx4 v[96:97], v[104:107], off
	v_pk_mul_f32 v[108:109], v[92:93], s[98:99] op_sel_hi:[1,0]
	v_pk_mul_f32 v[110:111], v[94:95], s[98:99] op_sel_hi:[1,0]
	v_or_b32_e32 v96, 32, v142
	v_exp_f32_e32 v108, v108
	v_exp_f32_e32 v109, v109
	v_exp_f32_e32 v110, v110
	v_exp_f32_e32 v111, v111
	s_nop 0
	v_pk_add_f32 v[108:109], v[108:109], 1.0 op_sel_hi:[1,0]
	v_pk_add_f32 v[110:111], v[110:111], 1.0 op_sel_hi:[1,0]
	v_rcp_f32_e32 v108, v108
	v_rcp_f32_e32 v109, v109
	v_rcp_f32_e32 v110, v110
	v_rcp_f32_e32 v111, v111
	s_nop 0
	v_pk_mul_f32 v[108:109], v[92:93], v[108:109]
	v_pk_mul_f32 v[110:111], v[94:95], v[110:111]
	v_pk_mul_f32 v[88:89], v[108:109], v[88:89]
	v_pk_mul_f32 v[90:91], v[110:111], v[90:91]
	v_cvt_pk_bf16_f32 v88, v88, v89
	v_cvt_pk_bf16_f32 v89, v90, v91
	v_pk_mul_f32 v[108:109], v[84:85], s[98:99] op_sel_hi:[1,0]
	v_pk_mul_f32 v[110:111], v[86:87], s[98:99] op_sel_hi:[1,0]
	v_exp_f32_e32 v108, v108
	v_exp_f32_e32 v109, v109
	v_exp_f32_e32 v110, v110
	v_exp_f32_e32 v111, v111
	s_nop 0
	v_pk_add_f32 v[108:109], v[108:109], 1.0 op_sel_hi:[1,0]
	v_pk_add_f32 v[110:111], v[110:111], 1.0 op_sel_hi:[1,0]
	v_rcp_f32_e32 v108, v108
	v_rcp_f32_e32 v109, v109
	v_rcp_f32_e32 v110, v110
	v_rcp_f32_e32 v111, v111
	s_nop 0
	v_pk_mul_f32 v[108:109], v[84:85], v[108:109]
	v_pk_mul_f32 v[110:111], v[86:87], v[110:111]
	v_pk_mul_f32 v[80:81], v[108:109], v[80:81]
	v_pk_mul_f32 v[82:83], v[110:111], v[82:83]
	v_cvt_pk_bf16_f32 v90, v80, v81
	v_cvt_pk_bf16_f32 v91, v82, v83
	v_mad_i64_i32 v[80:81], s[16:17], v96, s35, v[112:113]
	v_lshl_add_u64 v[80:81], v[80:81], 0, v[114:115]
	global_store_dwordx4 v[80:81], v[88:91], off
	v_pk_mul_f32 v[92:93], v[76:77], s[98:99] op_sel_hi:[1,0]
	v_pk_mul_f32 v[94:95], v[78:79], s[98:99] op_sel_hi:[1,0]
	v_or_b32_e32 v80, 48, v142
	v_exp_f32_e32 v92, v92
	v_exp_f32_e32 v93, v93
	v_exp_f32_e32 v94, v94
	v_exp_f32_e32 v95, v95
	s_nop 0
	v_pk_add_f32 v[92:93], v[92:93], 1.0 op_sel_hi:[1,0]
	v_pk_add_f32 v[94:95], v[94:95], 1.0 op_sel_hi:[1,0]
	v_rcp_f32_e32 v92, v92
	v_rcp_f32_e32 v93, v93
	v_rcp_f32_e32 v94, v94
	v_rcp_f32_e32 v95, v95
	s_nop 0
	v_pk_mul_f32 v[92:93], v[76:77], v[92:93]
	v_pk_mul_f32 v[94:95], v[78:79], v[94:95]
	v_pk_mul_f32 v[72:73], v[92:93], v[72:73]
	v_pk_mul_f32 v[74:75], v[94:95], v[74:75]
	v_cvt_pk_bf16_f32 v72, v72, v73
	v_cvt_pk_bf16_f32 v73, v74, v75
	v_pk_mul_f32 v[92:93], v[68:69], s[98:99] op_sel_hi:[1,0]
	v_pk_mul_f32 v[94:95], v[70:71], s[98:99] op_sel_hi:[1,0]
	v_exp_f32_e32 v92, v92
	v_exp_f32_e32 v93, v93
	v_exp_f32_e32 v94, v94
	v_exp_f32_e32 v95, v95
	s_nop 0
	v_pk_add_f32 v[92:93], v[92:93], 1.0 op_sel_hi:[1,0]
	v_pk_add_f32 v[94:95], v[94:95], 1.0 op_sel_hi:[1,0]
	v_rcp_f32_e32 v92, v92
	v_rcp_f32_e32 v93, v93
	v_rcp_f32_e32 v94, v94
	v_rcp_f32_e32 v95, v95
	s_nop 0
	v_pk_mul_f32 v[92:93], v[68:69], v[92:93]
	v_pk_mul_f32 v[94:95], v[70:71], v[94:95]
	v_pk_mul_f32 v[64:65], v[92:93], v[64:65]
	v_pk_mul_f32 v[66:67], v[94:95], v[66:67]
	v_cvt_pk_bf16_f32 v74, v64, v65
	v_cvt_pk_bf16_f32 v75, v66, v67
	v_mad_i64_i32 v[64:65], s[16:17], v80, s35, v[112:113]
	v_lshl_add_u64 v[64:65], v[64:65], 0, v[114:115]
	global_store_dwordx4 v[64:65], v[72:75], off
	v_pk_mul_f32 v[76:77], v[60:61], s[98:99] op_sel_hi:[1,0]
	v_pk_mul_f32 v[78:79], v[62:63], s[98:99] op_sel_hi:[1,0]
	v_add_u32_e32 v64, 0x80, v142
	v_exp_f32_e32 v76, v76
	v_exp_f32_e32 v77, v77
	v_exp_f32_e32 v78, v78
	v_exp_f32_e32 v79, v79
	s_nop 0
	v_pk_add_f32 v[76:77], v[76:77], 1.0 op_sel_hi:[1,0]
	v_pk_add_f32 v[78:79], v[78:79], 1.0 op_sel_hi:[1,0]
	v_rcp_f32_e32 v76, v76
	v_rcp_f32_e32 v77, v77
	v_rcp_f32_e32 v78, v78
	v_rcp_f32_e32 v79, v79
	s_nop 0
	v_pk_mul_f32 v[76:77], v[60:61], v[76:77]
	v_pk_mul_f32 v[78:79], v[62:63], v[78:79]
	v_pk_mul_f32 v[56:57], v[76:77], v[56:57]
	v_pk_mul_f32 v[58:59], v[78:79], v[58:59]
	v_cvt_pk_bf16_f32 v56, v56, v57
	v_cvt_pk_bf16_f32 v57, v58, v59
	v_pk_mul_f32 v[76:77], v[52:53], s[98:99] op_sel_hi:[1,0]
	v_pk_mul_f32 v[78:79], v[54:55], s[98:99] op_sel_hi:[1,0]
	v_exp_f32_e32 v76, v76
	v_exp_f32_e32 v77, v77
	v_exp_f32_e32 v78, v78
	v_exp_f32_e32 v79, v79
	s_nop 0
	v_pk_add_f32 v[76:77], v[76:77], 1.0 op_sel_hi:[1,0]
	v_pk_add_f32 v[78:79], v[78:79], 1.0 op_sel_hi:[1,0]
	v_rcp_f32_e32 v76, v76
	v_rcp_f32_e32 v77, v77
	v_rcp_f32_e32 v78, v78
	v_rcp_f32_e32 v79, v79
	s_nop 0
	v_pk_mul_f32 v[76:77], v[52:53], v[76:77]
	v_pk_mul_f32 v[78:79], v[54:55], v[78:79]
	v_pk_mul_f32 v[48:49], v[76:77], v[48:49]
	v_pk_mul_f32 v[50:51], v[78:79], v[50:51]
	v_cvt_pk_bf16_f32 v58, v48, v49
	v_cvt_pk_bf16_f32 v59, v50, v51
	v_mad_i64_i32 v[48:49], s[16:17], v64, s35, v[112:113]
	v_lshl_add_u64 v[48:49], v[48:49], 0, v[114:115]
	global_store_dwordx4 v[48:49], v[56:59], off
	v_pk_mul_f32 v[60:61], v[44:45], s[98:99] op_sel_hi:[1,0]
	v_pk_mul_f32 v[62:63], v[46:47], s[98:99] op_sel_hi:[1,0]
	v_add_u32_e32 v48, 0x90, v142
	v_exp_f32_e32 v60, v60
	v_exp_f32_e32 v61, v61
	v_exp_f32_e32 v62, v62
	v_exp_f32_e32 v63, v63
	s_nop 0
	v_pk_add_f32 v[60:61], v[60:61], 1.0 op_sel_hi:[1,0]
	v_pk_add_f32 v[62:63], v[62:63], 1.0 op_sel_hi:[1,0]
	v_rcp_f32_e32 v60, v60
	v_rcp_f32_e32 v61, v61
	v_rcp_f32_e32 v62, v62
	v_rcp_f32_e32 v63, v63
	s_nop 0
	v_pk_mul_f32 v[60:61], v[44:45], v[60:61]
	v_pk_mul_f32 v[62:63], v[46:47], v[62:63]
	v_pk_mul_f32 v[40:41], v[60:61], v[40:41]
	v_pk_mul_f32 v[42:43], v[62:63], v[42:43]
	v_cvt_pk_bf16_f32 v40, v40, v41
	v_cvt_pk_bf16_f32 v41, v42, v43
	v_pk_mul_f32 v[60:61], v[36:37], s[98:99] op_sel_hi:[1,0]
	v_pk_mul_f32 v[62:63], v[38:39], s[98:99] op_sel_hi:[1,0]
	v_exp_f32_e32 v60, v60
	v_exp_f32_e32 v61, v61
	v_exp_f32_e32 v62, v62
	v_exp_f32_e32 v63, v63
	s_nop 0
	v_pk_add_f32 v[60:61], v[60:61], 1.0 op_sel_hi:[1,0]
	v_pk_add_f32 v[62:63], v[62:63], 1.0 op_sel_hi:[1,0]
	v_rcp_f32_e32 v60, v60
	v_rcp_f32_e32 v61, v61
	v_rcp_f32_e32 v62, v62
	v_rcp_f32_e32 v63, v63
	s_nop 0
	v_pk_mul_f32 v[60:61], v[36:37], v[60:61]
	v_pk_mul_f32 v[62:63], v[38:39], v[62:63]
	v_pk_mul_f32 v[32:33], v[60:61], v[32:33]
	v_pk_mul_f32 v[34:35], v[62:63], v[34:35]
	v_cvt_pk_bf16_f32 v42, v32, v33
	v_cvt_pk_bf16_f32 v43, v34, v35
	v_mad_i64_i32 v[32:33], s[16:17], v48, s35, v[112:113]
	v_lshl_add_u64 v[32:33], v[32:33], 0, v[114:115]
	global_store_dwordx4 v[32:33], v[40:43], off
	v_pk_mul_f32 v[44:45], v[28:29], s[98:99] op_sel_hi:[1,0]
	v_pk_mul_f32 v[46:47], v[30:31], s[98:99] op_sel_hi:[1,0]
	v_add_u32_e32 v32, 0xa0, v142
	v_exp_f32_e32 v44, v44
	v_exp_f32_e32 v45, v45
	v_exp_f32_e32 v46, v46
	v_exp_f32_e32 v47, v47
	s_nop 0
	v_pk_add_f32 v[44:45], v[44:45], 1.0 op_sel_hi:[1,0]
	v_pk_add_f32 v[46:47], v[46:47], 1.0 op_sel_hi:[1,0]
	v_rcp_f32_e32 v44, v44
	v_rcp_f32_e32 v45, v45
	v_rcp_f32_e32 v46, v46
	v_rcp_f32_e32 v47, v47
	s_nop 0
	v_pk_mul_f32 v[44:45], v[28:29], v[44:45]
	v_pk_mul_f32 v[46:47], v[30:31], v[46:47]
	v_pk_mul_f32 v[24:25], v[44:45], v[24:25]
	v_pk_mul_f32 v[26:27], v[46:47], v[26:27]
	v_cvt_pk_bf16_f32 v24, v24, v25
	v_cvt_pk_bf16_f32 v25, v26, v27
	v_pk_mul_f32 v[44:45], v[20:21], s[98:99] op_sel_hi:[1,0]
	v_pk_mul_f32 v[46:47], v[22:23], s[98:99] op_sel_hi:[1,0]
	v_exp_f32_e32 v44, v44
	v_exp_f32_e32 v45, v45
	v_exp_f32_e32 v46, v46
	v_exp_f32_e32 v47, v47
	s_nop 0
	v_pk_add_f32 v[44:45], v[44:45], 1.0 op_sel_hi:[1,0]
	v_pk_add_f32 v[46:47], v[46:47], 1.0 op_sel_hi:[1,0]
	v_rcp_f32_e32 v44, v44
	v_rcp_f32_e32 v45, v45
	v_rcp_f32_e32 v46, v46
	v_rcp_f32_e32 v47, v47
	s_nop 0
	v_pk_mul_f32 v[44:45], v[20:21], v[44:45]
	v_pk_mul_f32 v[46:47], v[22:23], v[46:47]
	v_pk_mul_f32 v[16:17], v[44:45], v[16:17]
	v_pk_mul_f32 v[18:19], v[46:47], v[18:19]
	v_cvt_pk_bf16_f32 v26, v16, v17
	v_cvt_pk_bf16_f32 v27, v18, v19
	v_mad_i64_i32 v[16:17], s[16:17], v32, s35, v[112:113]
	v_lshl_add_u64 v[16:17], v[16:17], 0, v[114:115]
	global_store_dwordx4 v[16:17], v[24:27], off
	v_pk_mul_f32 v[28:29], v[12:13], s[98:99] op_sel_hi:[1,0]
	v_pk_mul_f32 v[30:31], v[14:15], s[98:99] op_sel_hi:[1,0]
	v_add_u32_e32 v16, 0xb0, v142
	v_exp_f32_e32 v28, v28
	v_exp_f32_e32 v29, v29
	v_exp_f32_e32 v30, v30
	v_exp_f32_e32 v31, v31
	s_nop 0
	v_pk_add_f32 v[28:29], v[28:29], 1.0 op_sel_hi:[1,0]
	v_pk_add_f32 v[30:31], v[30:31], 1.0 op_sel_hi:[1,0]
	v_rcp_f32_e32 v28, v28
	v_rcp_f32_e32 v29, v29
	v_rcp_f32_e32 v30, v30
	v_rcp_f32_e32 v31, v31
	s_nop 0
	v_pk_mul_f32 v[28:29], v[12:13], v[28:29]
	v_pk_mul_f32 v[30:31], v[14:15], v[30:31]
	v_pk_mul_f32 v[8:9], v[28:29], v[8:9]
	v_pk_mul_f32 v[10:11], v[30:31], v[10:11]
	v_cvt_pk_bf16_f32 v8, v8, v9
	v_cvt_pk_bf16_f32 v9, v10, v11
	v_pk_mul_f32 v[28:29], v[4:5], s[98:99] op_sel_hi:[1,0]
	v_pk_mul_f32 v[30:31], v[6:7], s[98:99] op_sel_hi:[1,0]
	v_exp_f32_e32 v28, v28
	v_exp_f32_e32 v29, v29
	v_exp_f32_e32 v30, v30
	v_exp_f32_e32 v31, v31
	s_nop 0
	v_pk_add_f32 v[28:29], v[28:29], 1.0 op_sel_hi:[1,0]
	v_pk_add_f32 v[30:31], v[30:31], 1.0 op_sel_hi:[1,0]
	v_rcp_f32_e32 v28, v28
	v_rcp_f32_e32 v29, v29
	v_rcp_f32_e32 v30, v30
	v_rcp_f32_e32 v31, v31
	s_nop 0
	v_pk_mul_f32 v[28:29], v[4:5], v[28:29]
	v_pk_mul_f32 v[30:31], v[6:7], v[30:31]
	v_pk_mul_f32 v[0:1], v[28:29], v[0:1]
	v_pk_mul_f32 v[2:3], v[30:31], v[2:3]
	v_cvt_pk_bf16_f32 v10, v0, v1
	v_cvt_pk_bf16_f32 v11, v2, v3
	v_mad_i64_i32 v[0:1], s[16:17], v16, s35, v[112:113]
	v_lshl_add_u64 v[0:1], v[0:1], 0, v[114:115]
	s_mov_b64 s[16:17], -1
	global_store_dwordx4 v[0:1], v[8:11], off
	s_cbranch_vccnz .LBB0_118
	s_andn2_b64 vcc, exec, s[8:9]
	s_cbranch_vccnz .LBB0_117
	s_barrier
	s_branch .LBB0_117
